# k13 plus redundant vmcnt wait ladders and post-wait nops removed from the MLA and diff attention loops
# speedup vs baseline: 1.0191x; 1.0000x over previous
; DI void finishSM(f32x16& p0, f32x16& p1, float alpha, float& l_reg, bf16x8& pa0, bf16x8& pa1, bf16x8& pa2, bf16x8& pa3) {
; #pragma unroll
;   for (int r = 0; r < 16; ++r) p1[r] = __builtin_amdgcn_exp2f(p1[r]);
;   float ps = 0;
; #pragma unroll
;   for (int r = 0; r < 16; ++r) ps += p0[r];
; #pragma unroll
;   for (int r = 0; r < 16; ++r) ps += p1[r];
;   { auto rr = __builtin_amdgcn_permlane32_swap(__float_as_uint(ps), __float_as_uint(ps), false, false);
;     ps = __uint_as_float(rr[0]) + __uint_as_float(rr[1]); }
;   l_reg = l_reg * alpha + ps;
;     ...
;   PK4(p0, 0, pa0); PK4(p0, 8, pa1); PK4(p1, 0, pa2); PK4(p1, 8, pa3);
.LBB0_748:
	ds_read_b128 v[66:69], v196
	ds_read_b128 v[70:73], v196 offset:12288
	ds_read_b128 v[198:201], v195
	ds_read_b128 v[202:205], v195 offset:12288
	v_add_f32_e32 v130, 0, v134
	v_add_f32_e32 v130, v135, v130
	s_waitcnt lgkmcnt(3)
	v_mfma_f32_32x32x16_bf16 v[82:97], v[66:69], v[110:113], 0
	v_add_f32_e32 v130, v136, v130
	v_add_f32_e32 v130, v138, v130
	v_add_f32_e32 v130, v155, v130
	v_add_f32_e32 v130, v156, v130
	v_add_f32_e32 v130, v137, v130
	v_add_f32_e32 v130, v154, v130
	v_add_f32_e32 v130, v131, v130
	s_waitcnt lgkmcnt(2)
	v_mfma_f32_32x32x16_bf16 v[66:81], v[70:73], v[110:113], 0
	v_add_f32_e32 v130, v133, v130
	v_add_f32_e32 v130, v139, v130
	v_add_f32_e32 v130, v152, v130
	v_exp_f32_e32 v126, v126
	v_add_f32_e32 v130, v132, v130
	v_exp_f32_e32 v127, v127
	v_add_f32_e32 v130, v140, v130
	s_waitcnt lgkmcnt(1)
	v_mfma_f32_32x32x16_bf16 v[82:97], v[198:201], v[106:109], v[82:97]
	v_exp_f32_e32 v124, v124
	v_add_f32_e32 v130, v141, v130
	v_exp_f32_e32 v125, v125
	v_add_f32_e32 v130, v153, v130
	v_exp_f32_e32 v122, v122
	v_add_f32_e32 v130, v126, v130
	v_exp_f32_e32 v123, v123
	s_waitcnt lgkmcnt(0)
	v_mfma_f32_32x32x16_bf16 v[66:81], v[202:205], v[106:109], v[66:81]
	ds_read_b128 v[198:201], v193
	ds_read_b128 v[202:205], v193 offset:12288
	v_add_f32_e32 v130, v127, v130
	v_exp_f32_e32 v118, v118
	v_add_f32_e32 v130, v124, v130
	v_exp_f32_e32 v119, v119
	v_add_f32_e32 v130, v125, v130
	v_exp_f32_e32 v116, v116
	s_waitcnt lgkmcnt(1)
	v_mfma_f32_32x32x16_bf16 v[82:97], v[198:201], v[102:105], v[82:97]
	v_add_f32_e32 v130, v122, v130
	v_exp_f32_e32 v117, v117
	v_add_f32_e32 v130, v123, v130
	v_exp_f32_e32 v128, v128
	v_add_f32_e32 v130, v118, v130
	v_exp_f32_e32 v129, v129
	v_add_f32_e32 v130, v119, v130
	s_waitcnt lgkmcnt(0)
	v_mfma_f32_32x32x16_bf16 v[66:81], v[202:205], v[102:105], v[66:81]
	ds_read_b128 v[198:201], v192
	ds_read_b128 v[202:205], v192 offset:12288
	v_exp_f32_e32 v120, v120
	v_add_f32_e32 v130, v116, v130
	v_exp_f32_e32 v121, v121
	v_add_f32_e32 v130, v117, v130
	v_exp_f32_e32 v114, v114
	v_add_f32_e32 v130, v128, v130
	s_waitcnt lgkmcnt(1)
	v_mfma_f32_32x32x16_bf16 v[82:97], v[198:201], v[98:101], v[82:97]
	v_exp_f32_e32 v115, v115
	v_add_f32_e32 v130, v129, v130
	v_add_f32_e32 v130, v120, v130
	v_add_f32_e32 v130, v121, v130
	v_add_f32_e32 v130, v114, v130
	v_cvt_pk_bf16_f32 v134, v134, v135
	v_cvt_pk_bf16_f32 v135, v136, v138
	s_waitcnt lgkmcnt(0)
	v_mfma_f32_32x32x16_bf16 v[66:81], v[202:205], v[98:101], v[66:81]
	ds_read_b128 v[198:201], v191
	ds_read_b128 v[202:205], v191 offset:12288
	ds_read_b128 v[206:209], v162
	v_cvt_pk_bf16_f32 v136, v155, v156
	v_cvt_pk_bf16_f32 v137, v137, v154
	s_nop 0
	v_permlane32_swap_b32_e32 v134, v136
	v_cvt_pk_bf16_f32 v138, v131, v133
	v_cvt_pk_bf16_f32 v139, v139, v152
	s_waitcnt lgkmcnt(0)
	v_mfma_f32_32x32x16_bf16 v[82:97], v[198:201], v[206:209], v[82:97]
	v_cvt_pk_bf16_f32 v140, v132, v140
	v_cvt_pk_bf16_f32 v141, v141, v153
	v_cvt_pk_bf16_f32 v214, v126, v127
	v_cvt_pk_bf16_f32 v215, v124, v125
	v_cvt_pk_bf16_f32 v216, v122, v123
	v_cvt_pk_bf16_f32 v217, v118, v119
	v_cvt_pk_bf16_f32 v218, v116, v117
	v_mfma_f32_32x32x16_bf16 v[66:81], v[202:205], v[206:209], v[66:81]
	ds_read_b128 v[198:201], v190
	ds_read_b128 v[202:205], v190 offset:12288
	ds_read_b128 v[206:209], v162 offset:1024
	v_cvt_pk_bf16_f32 v219, v128, v129
	v_cvt_pk_bf16_f32 v220, v120, v121
	v_cvt_pk_bf16_f32 v221, v114, v115
	v_permlane32_swap_b32_e32 v135, v137
	v_permlane32_swap_b32_e32 v138, v140
	s_waitcnt lgkmcnt(0)
	v_mfma_f32_32x32x16_bf16 v[82:97], v[198:201], v[206:209], v[82:97]
	v_permlane32_swap_b32_e32 v139, v141
	v_permlane32_swap_b32_e32 v214, v216
	v_permlane32_swap_b32_e32 v215, v217
	v_permlane32_swap_b32_e32 v218, v220
	v_mfma_f32_32x32x16_bf16 v[66:81], v[202:205], v[206:209], v[66:81]
	ds_read_b128 v[198:201], v189
	ds_read_b128 v[202:205], v189 offset:12288
	ds_read_b128 v[206:209], v162 offset:2048
	v_permlane32_swap_b32_e32 v219, v221
	s_waitcnt lgkmcnt(0)
	v_mfma_f32_32x32x16_bf16 v[82:97], v[198:201], v[206:209], v[82:97]
	v_mfma_f32_32x32x16_bf16 v[66:81], v[202:205], v[206:209], v[66:81]
	ds_read_b128 v[198:201], v188
	ds_read_b128 v[202:205], v188 offset:12288
	ds_read_b128 v[206:209], v162 offset:3072
	s_waitcnt lgkmcnt(0)
	v_mfma_f32_32x32x16_bf16 v[82:97], v[198:201], v[206:209], v[82:97]
	v_mfma_f32_32x32x16_bf16 v[66:81], v[202:205], v[206:209], v[66:81]
	ds_read_b128 v[198:201], v187
	ds_read_b128 v[202:205], v187 offset:12288
	ds_read_b128 v[206:209], v162 offset:4096
	s_waitcnt lgkmcnt(0)
	v_mfma_f32_32x32x16_bf16 v[82:97], v[198:201], v[206:209], v[82:97]
	v_mfma_f32_32x32x16_bf16 v[66:81], v[202:205], v[206:209], v[66:81]
	ds_read_b128 v[198:201], v186
	ds_read_b128 v[202:205], v186 offset:12288
	ds_read_b128 v[206:209], v162 offset:5120
	s_waitcnt lgkmcnt(0)
	v_mfma_f32_32x32x16_bf16 v[82:97], v[198:201], v[206:209], v[82:97]
	v_mfma_f32_32x32x16_bf16 v[66:81], v[202:205], v[206:209], v[66:81]
	ds_read_b128 v[198:201], v185
	ds_read_b128 v[202:205], v185 offset:12288
	ds_read_b128 v[206:209], v162 offset:6144
	s_waitcnt lgkmcnt(0)
	v_mfma_f32_32x32x16_bf16 v[82:97], v[198:201], v[206:209], v[82:97]
	v_mfma_f32_32x32x16_bf16 v[66:81], v[202:205], v[206:209], v[66:81]
	ds_read_b128 v[198:201], v184
	ds_read_b128 v[202:205], v184 offset:12288
	ds_read_b128 v[206:209], v162 offset:7168
	s_waitcnt lgkmcnt(0)
; #define SBAR() __builtin_amdgcn_sched_barrier(0)
; template <int OFF> DI s16x4 tr_read(int vb) { s16x4 r; asm volatile("ds_read_b64_tr_b16 %0, %1 offset:%2" : "=&v"(r) : "v"(vb), "i"(OFF) : "memory"); return r; }
; template <int D0> DI void pv_one(f32x16& od, int vb, bf16x8 pa0, bf16x8 pa1, bf16x8 pa2, bf16x8 pa3) {
;   const s16x4 l0 = tr_read<v_rd_off(D0, 0, 0)>(vb), h0 = tr_read<v_rd_off(D0, 0, 1)>(vb), l1 = tr_read<v_rd_off(D0, 1, 0)>(vb), h1 = tr_read<v_rd_off(D0, 1, 1)>(vb);
;   const s16x4 l2 = tr_read<v_rd_off(D0, 2, 0)>(vb), h2 = tr_read<v_rd_off(D0, 2, 1)>(vb), l3 = tr_read<v_rd_off(D0, 3, 0)>(vb), h3 = tr_read<v_rd_off(D0, 3, 1)>(vb);
;   asm volatile("s_waitcnt lgkmcnt(0)" ::: "memory"); SBAR();
;     ...
;   od = __builtin_amdgcn_mfma_f32_32x32x16_bf16(pa0, PK(l0, h0), od, 0, 0, 0);
;   od = __builtin_amdgcn_mfma_f32_32x32x16_bf16(pa1, PK(l1, h1), od, 0, 0, 0);
;   od = __builtin_amdgcn_mfma_f32_32x32x16_bf16(pa2, PK(l2, h2), od, 0, 0, 0);
;   od = __builtin_amdgcn_mfma_f32_32x32x16_bf16(pa3, PK(l3, h3), od, 0, 0, 0);
;     ...
; }
; DI void pv_d0(f32x16* o, int vb, bf16x8 pa0, bf16x8 pa1, bf16x8 pa2, bf16x8 pa3) {
;   pv_one<0>(o[0], vb, pa0, pa1, pa2, pa3); pv_one<1>(o[1], vb, pa0, pa1, pa2, pa3); pv_one<2>(o[2], vb, pa0, pa1, pa2, pa3); pv_one<3>(o[3], vb, pa0, pa1, pa2, pa3);
; template <int DQK, int SDEPTH, bool OUT_BF16, int QREG = DQK / 16, bool OUT_F16 = false> ...
;     ...
;   f32x16 pA0, pA1, pB0, pB1; float mnA, mnB, alA, alB; bf16x8 pa0, pa1, pa2, pa3; const int NT = seq / KVBLK;
;   constexpr int SE = 0, SO = SDEPTH - 1;
;   SLOAD(SE, 0); asm volatile("s_waitcnt vmcnt(0)" ::: "memory"); SWRITE(0, SE); __syncthreads();
;   QKT(pA0, pA1, K_lds); partialSM(pA0, pA1, m_reg, mnA, alA, SCALE);
;   SLOAD(SO, KVBLK); if constexpr (SDEPTH == 2) { if (2 < NT) SLOAD(SE, 2 * KVBLK); }
;   SWAIT(); SWRITE(1, SO); __syncthreads();
;   for (int j = 1; j + 1 < NT; j += 2) {
;     SBAR(); QKT(pB0, pB1, K_lds + SHM_K);
;     finishSM(pA0, pA1, alA, l_reg, pa0, pa1, pa2, pa3); SBAR();
;     SLOAD(SO, (j + SDEPTH) * KVBLK); SBAR();
;     pv_d0(o, vb0, pa0, pa1, pa2, pa3); partialSM(pB0, pB1, m_reg, mnB, alB, SCALE);
;     __syncthreads(); SWAIT(); SWRITE(0, SE);
;     RESC(alB); __syncthreads();
	v_mfma_f32_32x32x16_bf16 v[82:97], v[198:201], v[206:209], v[82:97]
	v_add_f32_e32 v198, v115, v130
	v_mov_b32_e32 v199, v198
	s_nop 1
	v_permlane32_swap_b32_e32 v198, v199
	global_load_dwordx4 v[114:117], v150, s[80:81]
	global_load_dwordx4 v[118:121], v150, s[82:83]
	global_load_dwordx4 v[122:125], v148, s[84:85]
	global_load_dwordx4 v[126:129], v146, s[84:85]
	global_load_dwordx4 v[130:133], v144, s[84:85]
	v_mfma_f32_32x32x16_bf16 v[66:81], v[202:205], v[206:209], v[66:81]
	ds_read_b64_tr_b16 v[200:201], v163 offset:0
	ds_read_b64_tr_b16 v[202:203], v163 offset:0x800
	ds_read_b64_tr_b16 v[204:205], v163 offset:0x1000
	ds_read_b64_tr_b16 v[206:207], v163 offset:0x1800
	ds_read_b64_tr_b16 v[208:209], v163 offset:0x2000
	ds_read_b64_tr_b16 v[210:211], v163 offset:0x2800
	ds_read_b64_tr_b16 v[222:223], v163 offset:0x3000
	ds_read_b64_tr_b16 v[224:225], v163 offset:0x3800
	s_waitcnt lgkmcnt(0)
	s_nop 0
	v_mfma_f32_32x32x16_bf16 v[2:17], v[134:137], v[200:203], v[2:17]
	ds_read_b64_tr_b16 v[200:201], v163 offset:0x200
	ds_read_b64_tr_b16 v[202:203], v163 offset:0xa00
	v_mfma_f32_32x32x16_bf16 v[2:17], v[138:141], v[204:207], v[2:17]
	ds_read_b64_tr_b16 v[204:205], v163 offset:0x1200
	ds_read_b64_tr_b16 v[206:207], v163 offset:0x1a00
	v_mfma_f32_32x32x16_bf16 v[2:17], v[214:217], v[208:211], v[2:17]
	ds_read_b64_tr_b16 v[208:209], v163 offset:0x2200
	ds_read_b64_tr_b16 v[210:211], v163 offset:0x2a00
	v_mfma_f32_32x32x16_bf16 v[2:17], v[218:221], v[222:225], v[2:17]
	ds_read_b64_tr_b16 v[222:223], v163 offset:0x3200
	ds_read_b64_tr_b16 v[224:225], v163 offset:0x3a00
	s_waitcnt lgkmcnt(0)
	v_mfma_f32_32x32x16_bf16 v[50:65], v[134:137], v[200:203], v[50:65]
	ds_read_b64_tr_b16 v[200:201], v163 offset:0x400
	ds_read_b64_tr_b16 v[202:203], v163 offset:0xc00
	v_mfma_f32_32x32x16_bf16 v[50:65], v[138:141], v[204:207], v[50:65]
	ds_read_b64_tr_b16 v[204:205], v163 offset:0x1400
	ds_read_b64_tr_b16 v[206:207], v163 offset:0x1c00
	v_mfma_f32_32x32x16_bf16 v[50:65], v[214:217], v[208:211], v[50:65]
	ds_read_b64_tr_b16 v[208:209], v163 offset:0x2400
	ds_read_b64_tr_b16 v[210:211], v163 offset:0x2c00
	v_mfma_f32_32x32x16_bf16 v[50:65], v[218:221], v[222:225], v[50:65]
	ds_read_b64_tr_b16 v[222:223], v163 offset:0x3400
	ds_read_b64_tr_b16 v[224:225], v163 offset:0x3c00
	s_waitcnt lgkmcnt(0)
	v_mfma_f32_32x32x16_bf16 v[34:49], v[134:137], v[200:203], v[34:49]
	ds_read_b64_tr_b16 v[200:201], v163 offset:0x600
	ds_read_b64_tr_b16 v[202:203], v163 offset:0xe00
	v_mfma_f32_32x32x16_bf16 v[34:49], v[138:141], v[204:207], v[34:49]
	ds_read_b64_tr_b16 v[204:205], v163 offset:0x1600
	ds_read_b64_tr_b16 v[206:207], v163 offset:0x1e00
	v_mfma_f32_32x32x16_bf16 v[34:49], v[214:217], v[208:211], v[34:49]
	ds_read_b64_tr_b16 v[208:209], v163 offset:0x2600
	ds_read_b64_tr_b16 v[210:211], v163 offset:0x2e00
	v_mfma_f32_32x32x16_bf16 v[34:49], v[218:221], v[222:225], v[34:49]
	ds_read_b64_tr_b16 v[222:223], v163 offset:0x3600
	ds_read_b64_tr_b16 v[224:225], v163 offset:0x3e00
	s_waitcnt lgkmcnt(0)
	v_mfma_f32_32x32x16_bf16 v[18:33], v[134:137], v[200:203], v[18:33]
	v_max_f32_e32 v134, v83, v83
	v_max_f32_e32 v135, v82, v82
	v_max_f32_e32 v134, v135, v134
	v_max3_f32 v134, v134, v84, v85
	v_max3_f32 v134, v134, v86, v87
	v_max3_f32 v134, v134, v88, v89
	v_max3_f32 v134, v134, v90, v91
	v_max3_f32 v134, v134, v92, v93
	v_max3_f32 v134, v134, v94, v95
	v_mfma_f32_32x32x16_bf16 v[18:33], v[138:141], v[204:207], v[18:33]
	v_max3_f32 v134, v134, v96, v97
	v_max3_f32 v134, v134, v66, v67
	v_max3_f32 v134, v134, v68, v69
	v_max3_f32 v134, v134, v70, v71
	v_max3_f32 v134, v134, v72, v73
	v_max3_f32 v134, v134, v74, v75
	v_max3_f32 v134, v134, v76, v77
	v_max3_f32 v134, v134, v78, v79
	v_mfma_f32_32x32x16_bf16 v[18:33], v[214:217], v[208:211], v[18:33]
	v_max3_f32 v134, v134, v80, v81
	v_mov_b32_e32 v135, v134
	s_nop 1
	v_permlane32_swap_b32_e32 v134, v135
	v_max_f32_e32 v135, v135, v135
	v_max_f32_e32 v134, v134, v134
	v_max_f32_e32 v134, v134, v135
	v_sub_f32_e32 v135, v134, v194
	v_cmp_ge_f32_e32 vcc, s96, v135
	v_max_f32_e32 v135, v194, v194
	v_max_f32_e32 v134, v135, v134
	v_mfma_f32_32x32x16_bf16 v[18:33], v[218:221], v[222:225], v[18:33]
	v_sub_f32_e32 v135, v194, v134
	v_mul_f32_e32 v135, 0x3dd53b94, v135
	s_barrier
	s_waitcnt vmcnt(0)
	ds_write_b128 v167, v[114:117]
	ds_write_b128 v168, v[118:121]
	ds_write_b128 v169, v[122:125] offset:32768
	ds_write_b128 v170, v[126:129] offset:32768
	ds_write_b128 v171, v[130:133] offset:32768
	v_exp_f32_e32 v114, v135
	s_cmp_eq_u64 vcc, exec
	s_cselect_b64 s[2:3], -1, 0
	v_cndmask_b32_e64 v200, v114, 1.0, s[2:3]
	v_cmp_gt_f32_e32 vcc, 1.0, v200
	s_cbranch_vccz .LBB0_752
	s_and_saveexec_b64 s[10:11], s[0:1]
	ds_write_b32 v164, v200 offset:128
	s_or_b64 exec, exec, s[10:11]
	s_waitcnt lgkmcnt(0)
	v_add_u32_e32 v126, v143, v0
	ds_read_b128 v[114:117], v126 offset:224
	ds_read_b128 v[118:121], v126 offset:192
	ds_read_b128 v[122:125], v126 offset:160
	ds_read_b128 v[126:129], v126 offset:128
	s_waitcnt lgkmcnt(3)
	v_pk_mul_f32 v[14:15], v[14:15], v[114:115]
	s_waitcnt lgkmcnt(2)
	v_pk_mul_f32 v[10:11], v[10:11], v[118:119]
	s_waitcnt lgkmcnt(1)
	v_pk_mul_f32 v[6:7], v[6:7], v[122:123]
	v_pk_mul_f32 v[16:17], v[16:17], v[116:117]
	v_pk_mul_f32 v[12:13], v[12:13], v[120:121]
	v_pk_mul_f32 v[8:9], v[8:9], v[124:125]
	s_waitcnt lgkmcnt(0)
	v_pk_mul_f32 v[4:5], v[4:5], v[128:129]
	v_pk_mul_f32 v[2:3], v[2:3], v[126:127]
	v_pk_mul_f32 v[62:63], v[62:63], v[114:115]
	v_pk_mul_f32 v[58:59], v[58:59], v[118:119]
	v_pk_mul_f32 v[54:55], v[54:55], v[122:123]
	v_pk_mul_f32 v[64:65], v[64:65], v[116:117]
	v_pk_mul_f32 v[60:61], v[60:61], v[120:121]
	v_pk_mul_f32 v[56:57], v[56:57], v[124:125]
	v_pk_mul_f32 v[52:53], v[52:53], v[128:129]
	v_pk_mul_f32 v[50:51], v[50:51], v[126:127]
	v_pk_mul_f32 v[46:47], v[46:47], v[114:115]
	v_pk_mul_f32 v[42:43], v[42:43], v[118:119]
	v_pk_mul_f32 v[38:39], v[38:39], v[122:123]
	v_pk_mul_f32 v[48:49], v[48:49], v[116:117]
	v_pk_mul_f32 v[44:45], v[44:45], v[120:121]
	v_pk_mul_f32 v[40:41], v[40:41], v[124:125]
	v_pk_mul_f32 v[36:37], v[36:37], v[128:129]
	v_pk_mul_f32 v[34:35], v[34:35], v[126:127]
	v_pk_mul_f32 v[30:31], v[30:31], v[114:115]
	v_pk_mul_f32 v[26:27], v[26:27], v[118:119]
	v_pk_mul_f32 v[22:23], v[22:23], v[122:123]
	v_pk_mul_f32 v[32:33], v[32:33], v[116:117]
	v_pk_mul_f32 v[28:29], v[28:29], v[120:121]
	v_pk_mul_f32 v[24:25], v[24:25], v[124:125]
	v_pk_mul_f32 v[20:21], v[20:21], v[128:129]
	v_pk_mul_f32 v[18:19], v[18:19], v[126:127]
; DI void partialSM(f32x16& p0, f32x16& p1, float& m_reg, float& mn, float& alpha, const float SCALE) {
;     ...
;   if (__builtin_expect(__all(pmax - m_reg <= THR / SCALE), 1)) { mn = m_reg; alpha = 1.f; }
;   else { mn = fmaxf(m_reg, pmax); alpha = __builtin_amdgcn_exp2f((m_reg - mn) * C); m_reg = mn; }
;   const float mnC = -mn * C;
; #pragma unroll
;   for (int r = 0; r < 16; ++r) p0[r] = fmaf(p0[r], C, mnC);
; #pragma unroll
;   for (int r = 0; r < 16; ++r) p1[r] = fmaf(p1[r], C, mnC);
; #pragma unroll
;   for (int r = 0; r < 16; ++r) p0[r] = __builtin_amdgcn_exp2f(p0[r]);
; }
; DI void finishSM(f32x16& p0, f32x16& p1, float alpha, float& l_reg, bf16x8& pa0, bf16x8& pa1, bf16x8& pa2, bf16x8& pa3) {
; #pragma unroll
;   for (int r = 0; r < 16; ++r) p1[r] = __builtin_amdgcn_exp2f(p1[r]);
;   float ps = 0;
; #pragma unroll
;   for (int r = 0; r < 16; ++r) ps += p0[r];
; #pragma unroll
;   for (int r = 0; r < 16; ++r) ps += p1[r];
;   { auto rr = __builtin_amdgcn_permlane32_swap(__float_as_uint(ps), __float_as_uint(ps), false, false);
;     ps = __uint_as_float(rr[0]) + __uint_as_float(rr[1]); }
;   l_reg = l_reg * alpha + ps;
;     ...
;   PK4(p0, 0, pa0); PK4(p0, 8, pa1); PK4(p1, 0, pa2); PK4(p1, 8, pa3);
.LBB0_752:
	v_cndmask_b32_e64 v194, v134, v194, s[2:3]
	v_mul_f32_e32 v130, 0xbdd53b94, v194
	v_fmamk_f32 v82, v82, 0x3dd53b94, v130
	v_fmamk_f32 v83, v83, 0x3dd53b94, v130
	v_fmamk_f32 v84, v84, 0x3dd53b94, v130
	v_fmamk_f32 v85, v85, 0x3dd53b94, v130
	v_fmamk_f32 v86, v86, 0x3dd53b94, v130
	v_fmamk_f32 v87, v87, 0x3dd53b94, v130
	v_fmamk_f32 v88, v88, 0x3dd53b94, v130
	v_fmamk_f32 v89, v89, 0x3dd53b94, v130
	v_fmamk_f32 v90, v90, 0x3dd53b94, v130
	v_fmamk_f32 v91, v91, 0x3dd53b94, v130
	v_fmamk_f32 v92, v92, 0x3dd53b94, v130
	v_fmamk_f32 v93, v93, 0x3dd53b94, v130
	v_fmamk_f32 v94, v94, 0x3dd53b94, v130
	v_fmamk_f32 v95, v95, 0x3dd53b94, v130
	v_fmamk_f32 v96, v96, 0x3dd53b94, v130
	v_fmamk_f32 v97, v97, 0x3dd53b94, v130
	v_fmamk_f32 v135, v66, 0x3dd53b94, v130
	v_fmamk_f32 v134, v68, 0x3dd53b94, v130
	v_fmamk_f32 v133, v70, 0x3dd53b94, v130
	v_fmamk_f32 v132, v72, 0x3dd53b94, v130
	v_fmamk_f32 v131, v74, 0x3dd53b94, v130
	v_fmamk_f32 v138, v76, 0x3dd53b94, v130
	v_fmamk_f32 v137, v78, 0x3dd53b94, v130
	v_fmamk_f32 v136, v80, 0x3dd53b94, v130
	v_fmamk_f32 v139, v67, 0x3dd53b94, v130
	v_fmamk_f32 v140, v69, 0x3dd53b94, v130
	v_fmamk_f32 v141, v71, 0x3dd53b94, v130
	v_fmamk_f32 v201, v73, 0x3dd53b94, v130
	v_fmamk_f32 v210, v75, 0x3dd53b94, v130
	v_fmamk_f32 v211, v77, 0x3dd53b94, v130
	v_fmamk_f32 v218, v79, 0x3dd53b94, v130
	v_fmac_f32_e32 v130, 0x3dd53b94, v81
	v_exp_f32_e32 v123, v82
	v_exp_f32_e32 v125, v83
	v_exp_f32_e32 v126, v84
	v_exp_f32_e32 v127, v85
	v_exp_f32_e32 v128, v86
	v_exp_f32_e32 v129, v87
	v_exp_f32_e32 v122, v88
	v_exp_f32_e32 v124, v89
	v_exp_f32_e32 v117, v90
	v_exp_f32_e32 v119, v91
	v_exp_f32_e32 v120, v92
	v_exp_f32_e32 v121, v93
	v_exp_f32_e32 v114, v94
	v_exp_f32_e32 v115, v95
	v_exp_f32_e32 v116, v96
	v_exp_f32_e32 v118, v97
	s_waitcnt lgkmcnt(0)
	s_barrier
	ds_read_b128 v[66:69], v172 offset:32768
	ds_read_b128 v[70:73], v172 offset:45056
	ds_read_b128 v[202:205], v173 offset:32768
	ds_read_b128 v[206:209], v173 offset:45056
	v_exp_f32_e32 v219, v140
	v_exp_f32_e32 v133, v133
	v_exp_f32_e32 v220, v141
	s_waitcnt lgkmcnt(3)
	v_mfma_f32_32x32x16_bf16 v[82:97], v[66:69], v[110:113], 0
	v_exp_f32_e32 v132, v132
	v_exp_f32_e32 v221, v201
	v_exp_f32_e32 v131, v131
	s_waitcnt lgkmcnt(2)
	v_mfma_f32_32x32x16_bf16 v[66:81], v[70:73], v[110:113], 0
	v_exp_f32_e32 v210, v210
	v_exp_f32_e32 v223, v138
	v_exp_f32_e32 v211, v211
	s_waitcnt lgkmcnt(1)
	v_mfma_f32_32x32x16_bf16 v[82:97], v[202:205], v[106:109], v[82:97]
	v_exp_f32_e32 v224, v137
	v_exp_f32_e32 v225, v218
	v_exp_f32_e32 v226, v136
	s_waitcnt lgkmcnt(0)
	v_mfma_f32_32x32x16_bf16 v[66:81], v[206:209], v[106:109], v[66:81]
	v_exp_f32_e32 v130, v130
	v_cvt_pk_bf16_f32 v136, v128, v129
	v_cvt_pk_bf16_f32 v137, v122, v124
	ds_read_b128 v[202:205], v174 offset:32768
	ds_read_b128 v[206:209], v174 offset:45056
	s_waitcnt lgkmcnt(1)
	v_mfma_f32_32x32x16_bf16 v[82:97], v[202:205], v[102:105], v[82:97]
	v_cvt_pk_bf16_f32 v138, v117, v119
	v_cvt_pk_bf16_f32 v140, v114, v115
	v_cvt_pk_bf16_f32 v141, v116, v118
	s_waitcnt lgkmcnt(0)
	v_mfma_f32_32x32x16_bf16 v[66:81], v[206:209], v[102:105], v[66:81]
	v_cvt_pk_bf16_f32 v222, v131, v210
	v_permlane32_swap_b32_e32 v138, v140
	v_exp_f32_e32 v246, v134
	ds_read_b128 v[202:205], v175 offset:32768
	ds_read_b128 v[206:209], v175 offset:45056
	s_waitcnt lgkmcnt(1)
	v_mfma_f32_32x32x16_bf16 v[82:97], v[202:205], v[98:101], v[82:97]
	v_add_f32_e32 v134, 0, v123
	v_add_f32_e32 v134, v125, v134
	v_add_f32_e32 v134, v126, v134
	s_waitcnt lgkmcnt(0)
	v_mfma_f32_32x32x16_bf16 v[66:81], v[206:209], v[98:101], v[66:81]
	v_add_f32_e32 v134, v127, v134
	v_add_f32_e32 v134, v128, v134
	v_add_f32_e32 v134, v129, v134
	ds_read_b128 v[202:205], v176 offset:32768
	ds_read_b128 v[206:209], v176 offset:45056
	ds_read_b128 v[214:217], v162
	s_waitcnt lgkmcnt(0)
	v_mfma_f32_32x32x16_bf16 v[82:97], v[202:205], v[214:217], v[82:97]
	v_add_f32_e32 v134, v122, v134
	v_add_f32_e32 v134, v124, v134
	v_add_f32_e32 v134, v117, v134
	v_mfma_f32_32x32x16_bf16 v[66:81], v[206:209], v[214:217], v[66:81]
	v_add_f32_e32 v134, v119, v134
	v_add_f32_e32 v134, v120, v134
	v_add_f32_e32 v134, v121, v134
	ds_read_b128 v[202:205], v177 offset:32768
	ds_read_b128 v[206:209], v177 offset:45056
	ds_read_b128 v[214:217], v162 offset:1024
	s_waitcnt lgkmcnt(0)
	v_mfma_f32_32x32x16_bf16 v[82:97], v[202:205], v[214:217], v[82:97]
	v_exp_f32_e32 v244, v135
	v_add_f32_e32 v134, v114, v134
	v_exp_f32_e32 v245, v139
	v_mfma_f32_32x32x16_bf16 v[66:81], v[206:209], v[214:217], v[66:81]
	v_add_f32_e32 v134, v115, v134
	v_add_f32_e32 v134, v116, v134
	v_add_f32_e32 v134, v118, v134
	v_add_f32_e32 v134, v244, v134
	ds_read_b128 v[202:205], v178 offset:32768
	ds_read_b128 v[206:209], v178 offset:45056
	ds_read_b128 v[214:217], v162 offset:2048
	s_waitcnt lgkmcnt(0)
	v_mfma_f32_32x32x16_bf16 v[82:97], v[202:205], v[214:217], v[82:97]
	v_add_f32_e32 v134, v245, v134
	v_add_f32_e32 v134, v246, v134
	v_add_f32_e32 v134, v219, v134
	v_mfma_f32_32x32x16_bf16 v[66:81], v[206:209], v[214:217], v[66:81]
	v_add_f32_e32 v134, v133, v134
	v_add_f32_e32 v134, v220, v134
	v_add_f32_e32 v134, v132, v134
	ds_read_b128 v[202:205], v179 offset:32768
	ds_read_b128 v[206:209], v179 offset:45056
	ds_read_b128 v[214:217], v162 offset:3072
	s_waitcnt lgkmcnt(0)
	v_mfma_f32_32x32x16_bf16 v[82:97], v[202:205], v[214:217], v[82:97]
	v_add_f32_e32 v134, v221, v134
	v_add_f32_e32 v134, v131, v134
	v_add_f32_e32 v134, v210, v134
	v_mfma_f32_32x32x16_bf16 v[66:81], v[206:209], v[214:217], v[66:81]
	v_add_f32_e32 v134, v223, v134
	v_add_f32_e32 v134, v211, v134
	v_add_f32_e32 v134, v224, v134
	ds_read_b128 v[202:205], v180 offset:32768
	ds_read_b128 v[206:209], v180 offset:45056
	ds_read_b128 v[214:217], v162 offset:4096
	s_waitcnt lgkmcnt(0)
; #define LAS __attribute__((address_space(3)))
; DI void finishSM(f32x16& p0, f32x16& p1, float alpha, float& l_reg, bf16x8& pa0, bf16x8& pa1, bf16x8& pa2, bf16x8& pa3) {
;     ...
;   PK4(p0, 0, pa0); PK4(p0, 8, pa1); PK4(p1, 0, pa2); PK4(p1, 8, pa3);
;     ...
; }
; template <int DQK> DI void qkt(f32x16& p0, f32x16& p1, const LAS char* Ks, const bf16x8* qr, int r32, int hi) {
;   p0 = f32x16{}; p1 = f32x16{};
; #pragma unroll
;   for (int d0 = 0; d0 < DQK / 16; ++d0) { const int cb = (d0 * 16 + hi * 8) * 2;
;     const bf16x8 b0 = *(const LAS bf16x8*)(Ks + kswz<DQK>(r32, cb));
;     const bf16x8 b1 = *(const LAS bf16x8*)(Ks + kswz<DQK>(32 + r32, cb));
;     p0 = __builtin_amdgcn_mfma_f32_32x32x16_bf16(b0, qr[d0], p0, 0, 0, 0);
;     p1 = __builtin_amdgcn_mfma_f32_32x32x16_bf16(b1, qr[d0], p1, 0, 0, 0); }
; }
; DI int v_st(int k, int c) { const int kk = (k & ~0xC) | ((k & 4) << 1) | ((k & 8) >> 1); return ((kk >> 3) * 4 + (c >> 5)) * 512 + ((kk & 7) * 32 + (c & 31)) * 2; }
; DI int v_rd_base(int lane) { return ((lane & 3) << 3) | (((lane >> 2) & 3) << 6) | (((lane >> 4) & 1) << 5) | (((lane >> 5) & 1) << 8); }
; template <int OFF> DI s16x4 tr_read(int vb) { s16x4 r; asm volatile("ds_read_b64_tr_b16 %0, %1 offset:%2" : "=&v"(r) : "v"(vb), "i"(OFF) : "memory"); return r; }
; template <int D0> DI void pv_one(f32x16& od, int vb, bf16x8 pa0, bf16x8 pa1, bf16x8 pa2, bf16x8 pa3) {
;   const s16x4 l0 = tr_read<v_rd_off(D0, 0, 0)>(vb), h0 = tr_read<v_rd_off(D0, 0, 1)>(vb), l1 = tr_read<v_rd_off(D0, 1, 0)>(vb), h1 = tr_read<v_rd_off(D0, 1, 1)>(vb);
;   const s16x4 l2 = tr_read<v_rd_off(D0, 2, 0)>(vb), h2 = tr_read<v_rd_off(D0, 2, 1)>(vb), l3 = tr_read<v_rd_off(D0, 3, 0)>(vb), h3 = tr_read<v_rd_off(D0, 3, 1)>(vb);
;   asm volatile("s_waitcnt lgkmcnt(0)" ::: "memory"); SBAR();
;     ...
;   od = __builtin_amdgcn_mfma_f32_32x32x16_bf16(pa0, PK(l0, h0), od, 0, 0, 0);
;   od = __builtin_amdgcn_mfma_f32_32x32x16_bf16(pa1, PK(l1, h1), od, 0, 0, 0);
;   od = __builtin_amdgcn_mfma_f32_32x32x16_bf16(pa2, PK(l2, h2), od, 0, 0, 0);
;   od = __builtin_amdgcn_mfma_f32_32x32x16_bf16(pa3, PK(l3, h3), od, 0, 0, 0);
;     ...
; }
; DI void pv_d0(f32x16* o, int vb, bf16x8 pa0, bf16x8 pa1, bf16x8 pa2, bf16x8 pa3) {
;   pv_one<0>(o[0], vb, pa0, pa1, pa2, pa3); pv_one<1>(o[1], vb, pa0, pa1, pa2, pa3); pv_one<2>(o[2], vb, pa0, pa1, pa2, pa3); pv_one<3>(o[3], vb, pa0, pa1, pa2, pa3);
; }
	v_mfma_f32_32x32x16_bf16 v[82:97], v[202:205], v[214:217], v[82:97]
	v_add_f32_e32 v134, v225, v134
	v_add_f32_e32 v134, v226, v134
	v_add_f32_e32 v201, v130, v134
	v_mfma_f32_32x32x16_bf16 v[66:81], v[206:209], v[214:217], v[66:81]
	v_cvt_pk_bf16_f32 v134, v123, v125
	s_nop 0
	v_cvt_pk_bf16_f32 v135, v126, v127
	ds_read_b128 v[202:205], v181 offset:32768
	ds_read_b128 v[206:209], v181 offset:45056
	ds_read_b128 v[214:217], v162 offset:5120
	s_waitcnt lgkmcnt(0)
	v_mfma_f32_32x32x16_bf16 v[82:97], v[202:205], v[214:217], v[82:97]
	v_permlane32_swap_b32_e32 v134, v136
	v_cvt_pk_bf16_f32 v139, v120, v121
	v_cvt_pk_bf16_f32 v218, v244, v245
	v_mfma_f32_32x32x16_bf16 v[66:81], v[206:209], v[214:217], v[66:81]
	v_cvt_pk_bf16_f32 v219, v246, v219
	v_cvt_pk_bf16_f32 v220, v133, v220
	v_cvt_pk_bf16_f32 v221, v132, v221
	ds_read_b128 v[202:205], v182 offset:32768
	ds_read_b128 v[206:209], v182 offset:45056
	ds_read_b128 v[214:217], v162 offset:6144
	s_waitcnt lgkmcnt(0)
	v_mfma_f32_32x32x16_bf16 v[82:97], v[202:205], v[214:217], v[82:97]
	v_cvt_pk_bf16_f32 v223, v223, v211
	v_cvt_pk_bf16_f32 v224, v224, v225
	v_cvt_pk_bf16_f32 v225, v226, v130
	v_mfma_f32_32x32x16_bf16 v[66:81], v[206:209], v[214:217], v[66:81]
	v_permlane32_swap_b32_e32 v135, v137
	v_permlane32_swap_b32_e32 v139, v141
	v_permlane32_swap_b32_e32 v218, v220
	ds_read_b128 v[202:205], v183 offset:32768
	ds_read_b128 v[206:209], v183 offset:45056
	ds_read_b128 v[214:217], v162 offset:7168
	s_waitcnt lgkmcnt(0)
	v_mfma_f32_32x32x16_bf16 v[82:97], v[202:205], v[214:217], v[82:97]
	v_permlane32_swap_b32_e32 v219, v221
	v_permlane32_swap_b32_e32 v222, v224
	v_permlane32_swap_b32_e32 v223, v225
	v_mov_b32_e32 v202, v201
	s_nop 1
	v_permlane32_swap_b32_e32 v201, v202
	v_mfma_f32_32x32x16_bf16 v[66:81], v[206:209], v[214:217], v[66:81]
	global_load_dwordx4 v[114:117], v150, s[86:87]
	global_load_dwordx4 v[118:121], v150, s[88:89]
	global_load_dwordx4 v[122:125], v148, s[90:91]
	global_load_dwordx4 v[126:129], v146, s[90:91]
	global_load_dwordx4 v[130:133], v144, s[90:91]
	ds_read_b64_tr_b16 v[152:153], v165 offset:0
	ds_read_b64_tr_b16 v[154:155], v165 offset:0x800
	ds_read_b64_tr_b16 v[156:157], v165 offset:0x1000
	ds_read_b64_tr_b16 v[158:159], v165 offset:0x1800
	ds_read_b64_tr_b16 v[204:205], v165 offset:0x2000
	ds_read_b64_tr_b16 v[206:207], v165 offset:0x2800
	ds_read_b64_tr_b16 v[208:209], v165 offset:0x3000
	ds_read_b64_tr_b16 v[210:211], v165 offset:0x3800
	s_waitcnt lgkmcnt(0)
	s_nop 0
	v_mfma_f32_32x32x16_bf16 v[2:17], v[134:137], v[152:155], v[2:17]
	ds_read_b64_tr_b16 v[152:153], v165 offset:0x200
	ds_read_b64_tr_b16 v[154:155], v165 offset:0xa00
	v_mfma_f32_32x32x16_bf16 v[2:17], v[138:141], v[156:159], v[2:17]
	ds_read_b64_tr_b16 v[156:157], v165 offset:0x1200
	ds_read_b64_tr_b16 v[158:159], v165 offset:0x1a00
	v_mfma_f32_32x32x16_bf16 v[2:17], v[218:221], v[204:207], v[2:17]
	ds_read_b64_tr_b16 v[204:205], v165 offset:0x2200
	ds_read_b64_tr_b16 v[206:207], v165 offset:0x2a00
	v_mfma_f32_32x32x16_bf16 v[2:17], v[222:225], v[208:211], v[2:17]
	ds_read_b64_tr_b16 v[208:209], v165 offset:0x3200
	ds_read_b64_tr_b16 v[210:211], v165 offset:0x3a00
	s_waitcnt lgkmcnt(0)
	v_mfma_f32_32x32x16_bf16 v[50:65], v[134:137], v[152:155], v[50:65]
	ds_read_b64_tr_b16 v[152:153], v165 offset:0x400
	ds_read_b64_tr_b16 v[154:155], v165 offset:0xc00
	v_mfma_f32_32x32x16_bf16 v[50:65], v[138:141], v[156:159], v[50:65]
	ds_read_b64_tr_b16 v[156:157], v165 offset:0x1400
	ds_read_b64_tr_b16 v[158:159], v165 offset:0x1c00
	v_mfma_f32_32x32x16_bf16 v[50:65], v[218:221], v[204:207], v[50:65]
	ds_read_b64_tr_b16 v[204:205], v165 offset:0x2400
	ds_read_b64_tr_b16 v[206:207], v165 offset:0x2c00
	v_mfma_f32_32x32x16_bf16 v[50:65], v[222:225], v[208:211], v[50:65]
	ds_read_b64_tr_b16 v[208:209], v165 offset:0x3400
	ds_read_b64_tr_b16 v[210:211], v165 offset:0x3c00
	s_waitcnt lgkmcnt(0)
	v_mfma_f32_32x32x16_bf16 v[34:49], v[134:137], v[152:155], v[34:49]
	ds_read_b64_tr_b16 v[152:153], v165 offset:0x600
	ds_read_b64_tr_b16 v[154:155], v165 offset:0xe00
	v_mfma_f32_32x32x16_bf16 v[34:49], v[138:141], v[156:159], v[34:49]
	ds_read_b64_tr_b16 v[156:157], v165 offset:0x1600
	ds_read_b64_tr_b16 v[158:159], v165 offset:0x1e00
	v_mfma_f32_32x32x16_bf16 v[34:49], v[218:221], v[204:207], v[34:49]
	ds_read_b64_tr_b16 v[204:205], v165 offset:0x2600
	ds_read_b64_tr_b16 v[206:207], v165 offset:0x2e00
	v_mfma_f32_32x32x16_bf16 v[34:49], v[222:225], v[208:211], v[34:49]
	ds_read_b64_tr_b16 v[208:209], v165 offset:0x3600
	ds_read_b64_tr_b16 v[210:211], v165 offset:0x3e00
	s_waitcnt lgkmcnt(0)
	v_mfma_f32_32x32x16_bf16 v[18:33], v[134:137], v[152:155], v[18:33]
	v_max_f32_e32 v134, v83, v83
	v_max_f32_e32 v135, v82, v82
	v_max_f32_e32 v134, v135, v134
	v_max3_f32 v134, v134, v84, v85
	v_max3_f32 v134, v134, v86, v87
	v_max3_f32 v134, v134, v88, v89
	v_max3_f32 v134, v134, v90, v91
	v_max3_f32 v134, v134, v92, v93
	v_max3_f32 v134, v134, v94, v95
	v_mfma_f32_32x32x16_bf16 v[18:33], v[138:141], v[156:159], v[18:33]
	v_max3_f32 v134, v134, v96, v97
	v_max3_f32 v134, v134, v66, v67
	v_max3_f32 v134, v134, v68, v69
	v_max3_f32 v134, v134, v70, v71
	v_max3_f32 v134, v134, v72, v73
	v_max3_f32 v134, v134, v74, v75
	v_max3_f32 v134, v134, v76, v77
	v_max3_f32 v134, v134, v78, v79
	v_mfma_f32_32x32x16_bf16 v[18:33], v[218:221], v[204:207], v[18:33]
	v_max3_f32 v134, v134, v80, v81
	v_mov_b32_e32 v135, v134
	s_nop 1
	v_permlane32_swap_b32_e32 v134, v135
	v_max_f32_e32 v135, v135, v135
	v_max_f32_e32 v134, v134, v134
	v_max_f32_e32 v134, v134, v135
	v_sub_f32_e32 v135, v134, v194
	v_cmp_ge_f32_e32 vcc, s96, v135
	v_max_f32_e32 v135, v194, v194
	v_max_f32_e32 v134, v135, v134
	v_mfma_f32_32x32x16_bf16 v[18:33], v[222:225], v[208:211], v[18:33]
	v_sub_f32_e32 v135, v194, v134
	v_mul_f32_e32 v135, 0x3dd53b94, v135
	s_barrier
; #define SWRITE(b, i) do { *(LAS bf16x8*)(V_lds + (b) * SHM_V + vst0) = sr_[i].vs0; *(LAS bf16x8*)(V_lds + (b) * SHM_V + vst1) = sr_[i].vs1; \
;     _Pragma("unroll") for (int _c = 0; _c < NKC; ++_c) *(LAS bf16x8*)(K_lds + (b) * SHM_K + kswz<DQK>(krow[_c], kcol[_c] * 2)) = sr_[i].ks[_c]; } while (0)
; #define SWAIT() do { if constexpr (SDEPTH == 2) { if constexpr (NKC == 1) asm volatile("s_waitcnt vmcnt(3)" ::: "memory"); else if constexpr (NKC == 2) asm volatile("s_waitcnt vmcnt(4)" ::: "memory"); else asm volatile("s_waitcnt vmcnt(5)" ::: "memory"); } \
;     else asm volatile("s_waitcnt vmcnt(0)" ::: "memory"); } while (0)
; #define RESC(a) do { if (__any((a) < 1.f)) { if (hi == 0) al_l[r32] = (a); asm volatile("s_waitcnt lgkmcnt(0)" ::: "memory"); \
;     _Pragma("unroll") for (int d = 0; d < 4; ++d) _Pragma("unroll") for (int r = 0; r < 16; ++r) o[d][r] *= al_l[crow(r, hi)]; } } while (0)
; template <int DQK, int SDEPTH, bool OUT_BF16, int QREG = DQK / 16, bool OUT_F16 = false> ...
;     ...
;     pv_d0(o, vb0 + SHM_V, pa0, pa1, pa2, pa3); partialSM(pA0, pA1, m_reg, mnA, alA, SCALE);
;     __syncthreads(); SWAIT(); SWRITE(1, SO);
;     RESC(alA); __syncthreads();
	s_waitcnt vmcnt(0)
	ds_write_b128 v167, v[114:117] offset:16384
	ds_write_b128 v168, v[118:121] offset:16384
	ds_write_b128 v169, v[122:125] offset:57344
	ds_write_b128 v170, v[126:129] offset:57344
	ds_write_b128 v171, v[130:133] offset:57344
	v_exp_f32_e32 v114, v135
	s_cmp_eq_u64 vcc, exec
	s_cselect_b64 s[2:3], -1, 0
	v_cndmask_b32_e64 v130, v114, 1.0, s[2:3]
	v_cmp_gt_f32_e32 vcc, 1.0, v130
	s_cbranch_vccz .LBB0_756
	s_and_saveexec_b64 s[10:11], s[0:1]
	ds_write_b32 v164, v130 offset:128
	s_or_b64 exec, exec, s[10:11]
	s_waitcnt lgkmcnt(0)
	v_add_u32_e32 v126, v143, v0
	ds_read_b128 v[114:117], v126 offset:224
	ds_read_b128 v[118:121], v126 offset:192
	ds_read_b128 v[122:125], v126 offset:160
	ds_read_b128 v[126:129], v126 offset:128
	s_waitcnt lgkmcnt(3)
	v_pk_mul_f32 v[14:15], v[14:15], v[114:115]
	s_waitcnt lgkmcnt(2)
	v_pk_mul_f32 v[10:11], v[10:11], v[118:119]
	s_waitcnt lgkmcnt(1)
	v_pk_mul_f32 v[6:7], v[6:7], v[122:123]
	v_pk_mul_f32 v[16:17], v[16:17], v[116:117]
	v_pk_mul_f32 v[12:13], v[12:13], v[120:121]
	v_pk_mul_f32 v[8:9], v[8:9], v[124:125]
	s_waitcnt lgkmcnt(0)
	v_pk_mul_f32 v[4:5], v[4:5], v[128:129]
	v_pk_mul_f32 v[2:3], v[2:3], v[126:127]
	v_pk_mul_f32 v[62:63], v[62:63], v[114:115]
	v_pk_mul_f32 v[58:59], v[58:59], v[118:119]
	v_pk_mul_f32 v[54:55], v[54:55], v[122:123]
	v_pk_mul_f32 v[64:65], v[64:65], v[116:117]
	v_pk_mul_f32 v[60:61], v[60:61], v[120:121]
	v_pk_mul_f32 v[56:57], v[56:57], v[124:125]
	v_pk_mul_f32 v[52:53], v[52:53], v[128:129]
	v_pk_mul_f32 v[50:51], v[50:51], v[126:127]
	v_pk_mul_f32 v[46:47], v[46:47], v[114:115]
	v_pk_mul_f32 v[42:43], v[42:43], v[118:119]
	v_pk_mul_f32 v[38:39], v[38:39], v[122:123]
	v_pk_mul_f32 v[48:49], v[48:49], v[116:117]
	v_pk_mul_f32 v[44:45], v[44:45], v[120:121]
	v_pk_mul_f32 v[40:41], v[40:41], v[124:125]
	v_pk_mul_f32 v[36:37], v[36:37], v[128:129]
	v_pk_mul_f32 v[34:35], v[34:35], v[126:127]
	v_pk_mul_f32 v[30:31], v[30:31], v[114:115]
	v_pk_mul_f32 v[26:27], v[26:27], v[118:119]
	v_pk_mul_f32 v[22:23], v[22:23], v[122:123]
	v_pk_mul_f32 v[32:33], v[32:33], v[116:117]
	v_pk_mul_f32 v[28:29], v[28:29], v[120:121]
	v_pk_mul_f32 v[24:25], v[24:25], v[124:125]
	v_pk_mul_f32 v[20:21], v[20:21], v[128:129]
	v_pk_mul_f32 v[18:19], v[18:19], v[126:127]

; #define LAS __attribute__((address_space(3)))
; DI void finishSM(f32x16& p0, f32x16& p1, float alpha, float& l_reg, bf16x8& pa0, bf16x8& pa1, bf16x8& pa2, bf16x8& pa3) {
; #pragma unroll
;   for (int r = 0; r < 16; ++r) p1[r] = __builtin_amdgcn_exp2f(p1[r]);
;   float ps = 0;
; #pragma unroll
;   for (int r = 0; r < 16; ++r) ps += p0[r];
; #pragma unroll
;   for (int r = 0; r < 16; ++r) ps += p1[r];
;   { auto rr = __builtin_amdgcn_permlane32_swap(__float_as_uint(ps), __float_as_uint(ps), false, false);
;     ps = __uint_as_float(rr[0]) + __uint_as_float(rr[1]); }
;   l_reg = l_reg * alpha + ps;
;     ...
;   PK4(p0, 0, pa0); PK4(p0, 8, pa1); PK4(p1, 0, pa2); PK4(p1, 8, pa3);
;     ...
; }
; template <int DQK> DI void qkt(f32x16& p0, f32x16& p1, const LAS char* Ks, const bf16x8* qr, int r32, int hi) {
;   p0 = f32x16{}; p1 = f32x16{};
; #pragma unroll
;   for (int d0 = 0; d0 < DQK / 16; ++d0) { const int cb = (d0 * 16 + hi * 8) * 2;
;     const bf16x8 b0 = *(const LAS bf16x8*)(Ks + kswz<DQK>(r32, cb));
;     const bf16x8 b1 = *(const LAS bf16x8*)(Ks + kswz<DQK>(32 + r32, cb));
;     p0 = __builtin_amdgcn_mfma_f32_32x32x16_bf16(b0, qr[d0], p0, 0, 0, 0);
;     p1 = __builtin_amdgcn_mfma_f32_32x32x16_bf16(b1, qr[d0], p1, 0, 0, 0); }
; }
; DI int v_st(int k, int c) { const int kk = (k & ~0xC) | ((k & 4) << 1) | ((k & 8) >> 1); return ((kk >> 3) * 4 + (c >> 5)) * 512 + ((kk & 7) * 32 + (c & 31)) * 2; }
; DI int v_rd_base(int lane) { return ((lane & 3) << 3) | (((lane >> 2) & 3) << 6) | (((lane >> 4) & 1) << 5) | (((lane >> 5) & 1) << 8); }
; template <int OFF> DI s16x4 tr_read(int vb) { s16x4 r; asm volatile("ds_read_b64_tr_b16 %0, %1 offset:%2" : "=&v"(r) : "v"(vb), "i"(OFF) : "memory"); return r; }
; template <int D0> DI void pv_one(f32x16& od, int vb, bf16x8 pa0, bf16x8 pa1, bf16x8 pa2, bf16x8 pa3) {
;   const s16x4 l0 = tr_read<v_rd_off(D0, 0, 0)>(vb), h0 = tr_read<v_rd_off(D0, 0, 1)>(vb), l1 = tr_read<v_rd_off(D0, 1, 0)>(vb), h1 = tr_read<v_rd_off(D0, 1, 1)>(vb);
;   const s16x4 l2 = tr_read<v_rd_off(D0, 2, 0)>(vb), h2 = tr_read<v_rd_off(D0, 2, 1)>(vb), l3 = tr_read<v_rd_off(D0, 3, 0)>(vb), h3 = tr_read<v_rd_off(D0, 3, 1)>(vb);
;   asm volatile("s_waitcnt lgkmcnt(0)" ::: "memory"); SBAR();
;     ...
;   od = __builtin_amdgcn_mfma_f32_32x32x16_bf16(pa0, PK(l0, h0), od, 0, 0, 0);
;   od = __builtin_amdgcn_mfma_f32_32x32x16_bf16(pa1, PK(l1, h1), od, 0, 0, 0);
.LBB0_782:
	ds_read_b128 v[66:69], v175 offset:40960
	ds_read_b128 v[70:73], v175 offset:45056
	ds_read_b128 v[188:191], v176 offset:40960
	ds_read_b128 v[192:195], v176 offset:45056
	v_add_f32_e32 v180, 0, v208
	v_add_f32_e32 v180, v209, v180
	v_cvt_pk_bf16_f32 v138, v208, v209
	v_add_f32_e32 v180, v210, v180
	v_add_f32_e32 v180, v211, v180
	s_waitcnt lgkmcnt(3)
	v_mfma_f32_32x32x16_bf16 v[82:97], v[66:69], v[110:113], 0
	v_cvt_pk_bf16_f32 v139, v210, v211
	v_add_f32_e32 v180, v214, v180
	v_add_f32_e32 v180, v215, v180
	v_cvt_pk_bf16_f32 v140, v214, v215
	v_add_f32_e32 v180, v216, v180
	v_add_f32_e32 v180, v217, v180
	v_cvt_pk_bf16_f32 v141, v216, v217
	s_waitcnt lgkmcnt(2)
	v_mfma_f32_32x32x16_bf16 v[66:81], v[70:73], v[110:113], 0
	v_add_f32_e32 v180, v218, v180
	v_add_f32_e32 v180, v219, v180
	v_cvt_pk_bf16_f32 v144, v218, v219
	v_add_f32_e32 v180, v220, v180
	v_add_f32_e32 v180, v221, v180
	v_cvt_pk_bf16_f32 v145, v220, v221
	s_waitcnt lgkmcnt(1)
	v_mfma_f32_32x32x16_bf16 v[82:97], v[188:191], v[106:109], v[82:97]
	v_add_f32_e32 v180, v222, v180
	v_add_f32_e32 v180, v223, v180
	v_cvt_pk_bf16_f32 v146, v222, v223
	v_add_f32_e32 v180, v224, v180
	v_add_f32_e32 v180, v225, v180
	v_cvt_pk_bf16_f32 v147, v224, v225
	s_waitcnt lgkmcnt(0)
	v_mfma_f32_32x32x16_bf16 v[66:81], v[192:195], v[106:109], v[66:81]
	ds_read_b128 v[188:191], v178 offset:40960
	ds_read_b128 v[192:195], v178 offset:45056
	v_add_f32_e32 v180, v226, v180
	v_add_f32_e32 v180, v227, v180
	v_cvt_pk_bf16_f32 v148, v226, v227
	v_add_f32_e32 v180, v228, v180
	v_add_f32_e32 v180, v229, v180
	v_cvt_pk_bf16_f32 v149, v228, v229
	s_waitcnt lgkmcnt(1)
	v_mfma_f32_32x32x16_bf16 v[82:97], v[188:191], v[102:105], v[82:97]
	v_add_f32_e32 v180, v230, v180
	v_add_f32_e32 v180, v231, v180
	v_cvt_pk_bf16_f32 v150, v230, v231
	v_add_f32_e32 v180, v244, v180
	v_add_f32_e32 v180, v245, v180
	v_cvt_pk_bf16_f32 v151, v244, v245
	s_waitcnt lgkmcnt(0)
	v_mfma_f32_32x32x16_bf16 v[66:81], v[192:195], v[102:105], v[66:81]
	ds_read_b128 v[188:191], v177 offset:40960
	ds_read_b128 v[192:195], v177 offset:45056
	v_add_f32_e32 v180, v246, v180
	v_add_f32_e32 v180, v247, v180
	v_cvt_pk_bf16_f32 v182, v246, v247
	v_add_f32_e32 v180, v248, v180
	v_add_f32_e32 v180, v249, v180
	v_cvt_pk_bf16_f32 v183, v248, v249
	s_waitcnt lgkmcnt(1)
	v_mfma_f32_32x32x16_bf16 v[82:97], v[188:191], v[98:101], v[82:97]
	v_add_f32_e32 v180, v250, v180
	v_add_f32_e32 v180, v251, v180
	v_cvt_pk_bf16_f32 v184, v250, v251
	v_add_f32_e32 v180, v252, v180
	v_add_f32_e32 v180, v202, v180
	v_cvt_pk_bf16_f32 v185, v252, v202
	v_mov_b32_e32 v181, v180
	s_waitcnt lgkmcnt(0)
	v_mfma_f32_32x32x16_bf16 v[66:81], v[192:195], v[98:101], v[66:81]
	v_permlane32_swap_b32_e32 v138, v140
	v_permlane32_swap_b32_e32 v139, v141
	v_permlane32_swap_b32_e32 v144, v146
	v_permlane32_swap_b32_e32 v145, v147
	v_permlane32_swap_b32_e32 v148, v150
	v_permlane32_swap_b32_e32 v149, v151
	v_permlane32_swap_b32_e32 v180, v181
	v_permlane32_swap_b32_e32 v182, v184
	v_permlane32_swap_b32_e32 v183, v185
	global_load_dwordx4 v[126:129], v158, s[80:81]
	global_load_dwordx4 v[130:133], v158, s[82:83]
	global_load_dwordx4 v[134:137], v160, s[84:85]
	ds_read_b64_tr_b16 v[186:187], v171 offset:0x0
	ds_read_b64_tr_b16 v[188:189], v171 offset:0x800
	ds_read_b64_tr_b16 v[190:191], v171 offset:0x1000
	ds_read_b64_tr_b16 v[192:193], v171 offset:0x1800
	ds_read_b64_tr_b16 v[194:195], v171 offset:0x2000
	ds_read_b64_tr_b16 v[196:197], v171 offset:0x2800
	ds_read_b64_tr_b16 v[198:199], v171 offset:0x3000
	ds_read_b64_tr_b16 v[200:201], v171 offset:0x3800
	s_waitcnt lgkmcnt(0)
	v_mfma_f32_32x32x16_bf16 v[2:17], v[138:141], v[186:189], v[2:17]
	ds_read_b64_tr_b16 v[186:187], v171 offset:0x200
	ds_read_b64_tr_b16 v[188:189], v171 offset:0xa00
	v_max3_f32 v203, v82, v83, v84
	v_max3_f32 v204, v85, v86, v87
	v_max3_f32 v203, v203, v88, v89
	v_max3_f32 v204, v204, v90, v91
	v_max3_f32 v203, v203, v92, v93
	v_max3_f32 v204, v204, v94, v95
	v_mfma_f32_32x32x16_bf16 v[2:17], v[144:147], v[190:193], v[2:17]
	ds_read_b64_tr_b16 v[190:191], v171 offset:0x1200
	ds_read_b64_tr_b16 v[192:193], v171 offset:0x1a00
	v_max3_f32 v203, v203, v96, v97
	v_max3_f32 v204, v204, v66, v67
	v_max3_f32 v203, v203, v68, v69
	v_max3_f32 v204, v204, v70, v71
	v_max3_f32 v203, v203, v72, v73
	v_max3_f32 v204, v204, v74, v75
	v_mfma_f32_32x32x16_bf16 v[2:17], v[148:151], v[194:197], v[2:17]
	ds_read_b64_tr_b16 v[194:195], v171 offset:0x2200
	ds_read_b64_tr_b16 v[196:197], v171 offset:0x2a00
	v_max3_f32 v203, v203, v76, v77
	v_max3_f32 v204, v204, v78, v79
	v_max3_f32 v203, v203, v80, v81
	v_max_f32_e32 v203, v203, v204
	v_mov_b32_e32 v204, v203
	v_mfma_f32_32x32x16_bf16 v[2:17], v[182:185], v[198:201], v[2:17]
	ds_read_b64_tr_b16 v[198:199], v171 offset:0x3200
	ds_read_b64_tr_b16 v[200:201], v171 offset:0x3a00
	v_permlane32_swap_b32_e32 v203, v204
	v_max_f32_e32 v203, v203, v204
	v_sub_f32_e32 v204, v203, v142
	v_cmp_ge_f32_e32 vcc, s26, v204
	v_max_f32_e32 v203, v142, v203
	v_sub_f32_e32 v204, v142, v203
	s_waitcnt lgkmcnt(0)
; #define SBAR() __builtin_amdgcn_sched_barrier(0)
; #define SLOAD(i, k0) do { sr_[i].vs0 = *reinterpret_cast<const bf16x8*>(&Vh[(long)((k0) + sr) * DV + sc]); sr_[i].vs1 = *reinterpret_cast<const bf16x8*>(&Vh[(long)((k0) + 32 + sr) * DV + sc]); \
;     _Pragma("unroll") for (int _c = 0; _c < NKC; ++_c) sr_[i].ks[_c] = *reinterpret_cast<const bf16x8*>(&Kh[(long)((k0) + krow[_c]) * DQK + kcol[_c]]); } while (0)
; #define SWRITE(b, i) do { *(LAS bf16x8*)(V_lds + (b) * SHM_V + vst0) = sr_[i].vs0; *(LAS bf16x8*)(V_lds + (b) * SHM_V + vst1) = sr_[i].vs1; \
;     _Pragma("unroll") for (int _c = 0; _c < NKC; ++_c) *(LAS bf16x8*)(K_lds + (b) * SHM_K + kswz<DQK>(krow[_c], kcol[_c] * 2)) = sr_[i].ks[_c]; } while (0)
; #define RESC(a) do { if (__any((a) < 1.f)) { if (hi == 0) al_l[r32] = (a); asm volatile("s_waitcnt lgkmcnt(0)" ::: "memory"); \
;     _Pragma("unroll") for (int d = 0; d < 4; ++d) _Pragma("unroll") for (int r = 0; r < 16; ++r) o[d][r] *= al_l[crow(r, hi)]; } } while (0)
; DI void partialSM(f32x16& p0, f32x16& p1, float& m_reg, float& mn, float& alpha, const float SCALE) {
;   const float C = SCALE * 1.4426950408889634f;
;   float pmax = p0[0];
; #pragma unroll
;   for (int r = 1; r < 16; ++r) pmax = fmaxf(pmax, p0[r]);
; #pragma unroll
;   for (int r = 0; r < 16; ++r) pmax = fmaxf(pmax, p1[r]);
;   { auto rr = __builtin_amdgcn_permlane32_swap(__float_as_uint(pmax), __float_as_uint(pmax), false, false);
;     pmax = fmaxf(__uint_as_float(rr[0]), __uint_as_float(rr[1])); }
;   if (__builtin_expect(__all(pmax - m_reg <= THR / SCALE), 1)) { mn = m_reg; alpha = 1.f; }
;   else { mn = fmaxf(m_reg, pmax); alpha = __builtin_amdgcn_exp2f((m_reg - mn) * C); m_reg = mn; }
;   const float mnC = -mn * C;
; #pragma unroll
;   for (int r = 0; r < 16; ++r) p0[r] = fmaf(p0[r], C, mnC);
; #pragma unroll
;   for (int r = 0; r < 16; ++r) p1[r] = fmaf(p1[r], C, mnC);
; #pragma unroll
;   for (int r = 0; r < 16; ++r) p0[r] = __builtin_amdgcn_exp2f(p0[r]);
; }
; template <int DQK, int SDEPTH, bool OUT_BF16, int QREG = DQK / 16, bool OUT_F16 = false> ...
;     ...
;     finishSM(pA0, pA1, alA, l_reg, pa0, pa1, pa2, pa3); SBAR();
;     SLOAD(SO, (j + SDEPTH) * KVBLK); SBAR();
;     pv_d0(o, vb0, pa0, pa1, pa2, pa3); partialSM(pB0, pB1, m_reg, mnB, alB, SCALE);
;     __syncthreads(); SWAIT(); SWRITE(0, SE);
;     RESC(alB); __syncthreads();
	v_mfma_f32_32x32x16_bf16 v[50:65], v[138:141], v[186:189], v[50:65]
	ds_read_b64_tr_b16 v[186:187], v171 offset:0x400
	ds_read_b64_tr_b16 v[188:189], v171 offset:0xc00
	v_mul_f32_e32 v204, 0x3e38aa3b, v204
	v_exp_f32_e32 v204, v204
	s_cmp_eq_u64 vcc, exec
	s_cselect_b64 s[2:3], -1, 0
	v_mfma_f32_32x32x16_bf16 v[50:65], v[144:147], v[190:193], v[50:65]
	ds_read_b64_tr_b16 v[190:191], v171 offset:0x1400
	ds_read_b64_tr_b16 v[192:193], v171 offset:0x1c00
	v_cndmask_b32_e64 v202, v203, v142, s[2:3]
	v_mul_f32_e32 v202, 0xbe38aa3b, v202
	v_fmamk_f32 v208, v82, 0x3e38aa3b, v202
	v_fmamk_f32 v209, v83, 0x3e38aa3b, v202
	v_fmamk_f32 v210, v84, 0x3e38aa3b, v202
	v_mfma_f32_32x32x16_bf16 v[50:65], v[148:151], v[194:197], v[50:65]
	ds_read_b64_tr_b16 v[194:195], v171 offset:0x2400
	ds_read_b64_tr_b16 v[196:197], v171 offset:0x2c00
	v_fmamk_f32 v211, v85, 0x3e38aa3b, v202
	v_fmamk_f32 v214, v86, 0x3e38aa3b, v202
	v_fmamk_f32 v215, v87, 0x3e38aa3b, v202
	v_exp_f32_e32 v208, v208
	v_exp_f32_e32 v209, v209
	v_exp_f32_e32 v210, v210
	v_mfma_f32_32x32x16_bf16 v[50:65], v[182:185], v[198:201], v[50:65]
	ds_read_b64_tr_b16 v[198:199], v171 offset:0x3400
	ds_read_b64_tr_b16 v[200:201], v171 offset:0x3c00
	v_fmamk_f32 v216, v88, 0x3e38aa3b, v202
	v_fmamk_f32 v217, v89, 0x3e38aa3b, v202
	v_fmamk_f32 v218, v90, 0x3e38aa3b, v202
	v_exp_f32_e32 v211, v211
	v_exp_f32_e32 v214, v214
	v_exp_f32_e32 v215, v215
	s_waitcnt lgkmcnt(0)
	v_mfma_f32_32x32x16_bf16 v[34:49], v[138:141], v[186:189], v[34:49]
	ds_read_b64_tr_b16 v[186:187], v171 offset:0x600
	ds_read_b64_tr_b16 v[188:189], v171 offset:0xe00
	v_fmamk_f32 v219, v91, 0x3e38aa3b, v202
	v_fmamk_f32 v220, v92, 0x3e38aa3b, v202
	v_fmamk_f32 v221, v93, 0x3e38aa3b, v202
	v_exp_f32_e32 v216, v216
	v_exp_f32_e32 v217, v217
	v_exp_f32_e32 v218, v218
	v_mfma_f32_32x32x16_bf16 v[34:49], v[144:147], v[190:193], v[34:49]
	ds_read_b64_tr_b16 v[190:191], v171 offset:0x1600
	ds_read_b64_tr_b16 v[192:193], v171 offset:0x1e00
	v_fmamk_f32 v222, v94, 0x3e38aa3b, v202
	v_fmamk_f32 v223, v95, 0x3e38aa3b, v202
	v_fmamk_f32 v224, v96, 0x3e38aa3b, v202
	v_exp_f32_e32 v219, v219
	v_exp_f32_e32 v220, v220
	v_exp_f32_e32 v221, v221
	v_mfma_f32_32x32x16_bf16 v[34:49], v[148:151], v[194:197], v[34:49]
	ds_read_b64_tr_b16 v[194:195], v171 offset:0x2600
	ds_read_b64_tr_b16 v[196:197], v171 offset:0x2e00
	v_fmamk_f32 v225, v97, 0x3e38aa3b, v202
	v_fmamk_f32 v226, v66, 0x3e38aa3b, v202
	v_fmamk_f32 v227, v67, 0x3e38aa3b, v202
	v_exp_f32_e32 v222, v222
	v_exp_f32_e32 v223, v223
	v_exp_f32_e32 v224, v224
	v_mfma_f32_32x32x16_bf16 v[34:49], v[182:185], v[198:201], v[34:49]
	ds_read_b64_tr_b16 v[198:199], v171 offset:0x3600
	ds_read_b64_tr_b16 v[200:201], v171 offset:0x3e00
	v_fmamk_f32 v228, v68, 0x3e38aa3b, v202
	v_fmamk_f32 v229, v69, 0x3e38aa3b, v202
	v_fmamk_f32 v230, v70, 0x3e38aa3b, v202
	v_exp_f32_e32 v225, v225
	v_exp_f32_e32 v226, v226
	v_exp_f32_e32 v227, v227
	s_waitcnt lgkmcnt(0)
	v_mfma_f32_32x32x16_bf16 v[18:33], v[138:141], v[186:189], v[18:33]
	v_fmamk_f32 v231, v71, 0x3e38aa3b, v202
	v_fmamk_f32 v244, v72, 0x3e38aa3b, v202
	v_fmamk_f32 v245, v73, 0x3e38aa3b, v202
	v_exp_f32_e32 v228, v228
	v_exp_f32_e32 v229, v229
	v_exp_f32_e32 v230, v230
	v_mfma_f32_32x32x16_bf16 v[18:33], v[144:147], v[190:193], v[18:33]
	v_fmamk_f32 v246, v74, 0x3e38aa3b, v202
	v_fmamk_f32 v247, v75, 0x3e38aa3b, v202
	v_fmamk_f32 v248, v76, 0x3e38aa3b, v202
	v_exp_f32_e32 v231, v231
	v_exp_f32_e32 v244, v244
	v_exp_f32_e32 v245, v245
	v_mfma_f32_32x32x16_bf16 v[18:33], v[148:151], v[194:197], v[18:33]
	v_fmamk_f32 v249, v77, 0x3e38aa3b, v202
	v_fmamk_f32 v250, v78, 0x3e38aa3b, v202
	v_fmamk_f32 v251, v79, 0x3e38aa3b, v202
	v_exp_f32_e32 v246, v246
	v_exp_f32_e32 v247, v247
	v_exp_f32_e32 v248, v248
	v_mfma_f32_32x32x16_bf16 v[18:33], v[182:185], v[198:201], v[18:33]
	v_fmamk_f32 v252, v80, 0x3e38aa3b, v202
	v_fmac_f32_e32 v202, 0x3e38aa3b, v81
	v_exp_f32_e32 v249, v249
	v_exp_f32_e32 v250, v250
	v_exp_f32_e32 v251, v251
	v_exp_f32_e32 v252, v252
	v_exp_f32_e32 v202, v202
	v_cndmask_b32_e64 v183, v203, v142, s[2:3]
	s_barrier
	s_waitcnt vmcnt(3)
	v_cndmask_b32_e64 v182, v204, 1.0, s[2:3]
	v_cmp_gt_f32_e32 vcc, 1.0, v182
	ds_write_b128 v172, v[114:117]
	ds_write_b128 v173, v[118:121]
	ds_write_b128 v174, v[122:125] offset:32768
	s_cbranch_vccz .LBB0_786
	s_and_saveexec_b64 s[10:11], s[0:1]
	ds_write_b32 v168, v182 offset:49280
	s_or_b64 exec, exec, s[10:11]
	s_waitcnt lgkmcnt(0)
	v_add_u32_e32 v139, v157, v0
	ds_read_b128 v[144:147], v139 offset:49376
	ds_read_b128 v[148:151], v139 offset:49344
	ds_read_b128 v[184:187], v139 offset:49312
	ds_read_b128 v[188:191], v139 offset:49280
	s_waitcnt lgkmcnt(3)
	v_pk_mul_f32 v[14:15], v[14:15], v[144:145]
	s_waitcnt lgkmcnt(2)
	v_pk_mul_f32 v[10:11], v[10:11], v[148:149]
	s_waitcnt lgkmcnt(1)
	v_pk_mul_f32 v[6:7], v[6:7], v[184:185]
	v_pk_mul_f32 v[16:17], v[16:17], v[146:147]
	v_pk_mul_f32 v[12:13], v[12:13], v[150:151]
	v_pk_mul_f32 v[8:9], v[8:9], v[186:187]
	s_waitcnt lgkmcnt(0)
	v_pk_mul_f32 v[4:5], v[4:5], v[190:191]
	v_pk_mul_f32 v[2:3], v[2:3], v[188:189]
	v_pk_mul_f32 v[62:63], v[62:63], v[144:145]
	v_pk_mul_f32 v[58:59], v[58:59], v[148:149]
	v_pk_mul_f32 v[54:55], v[54:55], v[184:185]
	v_pk_mul_f32 v[64:65], v[64:65], v[146:147]
	v_pk_mul_f32 v[60:61], v[60:61], v[150:151]
	v_pk_mul_f32 v[56:57], v[56:57], v[186:187]
	v_pk_mul_f32 v[52:53], v[52:53], v[190:191]
	v_pk_mul_f32 v[50:51], v[50:51], v[188:189]
	v_pk_mul_f32 v[46:47], v[46:47], v[144:145]
	v_pk_mul_f32 v[42:43], v[42:43], v[148:149]
	v_pk_mul_f32 v[38:39], v[38:39], v[184:185]
	v_pk_mul_f32 v[48:49], v[48:49], v[146:147]
	v_pk_mul_f32 v[44:45], v[44:45], v[150:151]
	v_pk_mul_f32 v[40:41], v[40:41], v[186:187]
	v_pk_mul_f32 v[36:37], v[36:37], v[190:191]
	v_pk_mul_f32 v[34:35], v[34:35], v[188:189]
	v_pk_mul_f32 v[30:31], v[30:31], v[144:145]
	v_pk_mul_f32 v[26:27], v[26:27], v[148:149]
	v_pk_mul_f32 v[22:23], v[22:23], v[184:185]
	v_pk_mul_f32 v[32:33], v[32:33], v[146:147]
	v_pk_mul_f32 v[28:29], v[28:29], v[150:151]
	v_pk_mul_f32 v[24:25], v[24:25], v[186:187]
	v_pk_mul_f32 v[20:21], v[20:21], v[190:191]
	v_pk_mul_f32 v[18:19], v[18:19], v[188:189]

; #define SBAR() __builtin_amdgcn_sched_barrier(0)
; template <int OFF> DI s16x4 tr_read(int vb) { s16x4 r; asm volatile("ds_read_b64_tr_b16 %0, %1 offset:%2" : "=&v"(r) : "v"(vb), "i"(OFF) : "memory"); return r; }
; DI void partialSM(f32x16& p0, f32x16& p1, float& m_reg, float& mn, float& alpha, const float SCALE) {
;   const float C = SCALE * 1.4426950408889634f;
;   float pmax = p0[0];
; #pragma unroll
;   for (int r = 1; r < 16; ++r) pmax = fmaxf(pmax, p0[r]);
; #pragma unroll
;   for (int r = 0; r < 16; ++r) pmax = fmaxf(pmax, p1[r]);
;   { auto rr = __builtin_amdgcn_permlane32_swap(__float_as_uint(pmax), __float_as_uint(pmax), false, false);
;     pmax = fmaxf(__uint_as_float(rr[0]), __uint_as_float(rr[1])); }
;   if (__builtin_expect(__all(pmax - m_reg <= THR / SCALE), 1)) { mn = m_reg; alpha = 1.f; }
;   else { mn = fmaxf(m_reg, pmax); alpha = __builtin_amdgcn_exp2f((m_reg - mn) * C); m_reg = mn; }
;   const float mnC = -mn * C;
; #pragma unroll
;   for (int r = 0; r < 16; ++r) p0[r] = fmaf(p0[r], C, mnC);
; #pragma unroll
;   for (int r = 0; r < 16; ++r) p1[r] = fmaf(p1[r], C, mnC);
; #pragma unroll
;   for (int r = 0; r < 16; ++r) p0[r] = __builtin_amdgcn_exp2f(p0[r]);
; }
; template <int D0> DI void pv_one(f32x16& od, int vb, bf16x8 pa0, bf16x8 pa1, bf16x8 pa2, bf16x8 pa3) {
;   const s16x4 l0 = tr_read<v_rd_off(D0, 0, 0)>(vb), h0 = tr_read<v_rd_off(D0, 0, 1)>(vb), l1 = tr_read<v_rd_off(D0, 1, 0)>(vb), h1 = tr_read<v_rd_off(D0, 1, 1)>(vb);
;   const s16x4 l2 = tr_read<v_rd_off(D0, 2, 0)>(vb), h2 = tr_read<v_rd_off(D0, 2, 1)>(vb), l3 = tr_read<v_rd_off(D0, 3, 0)>(vb), h3 = tr_read<v_rd_off(D0, 3, 1)>(vb);
;   asm volatile("s_waitcnt lgkmcnt(0)" ::: "memory"); SBAR();
;     ...
;   od = __builtin_amdgcn_mfma_f32_32x32x16_bf16(pa0, PK(l0, h0), od, 0, 0, 0);
;   od = __builtin_amdgcn_mfma_f32_32x32x16_bf16(pa1, PK(l1, h1), od, 0, 0, 0);
;   od = __builtin_amdgcn_mfma_f32_32x32x16_bf16(pa2, PK(l2, h2), od, 0, 0, 0);
;   od = __builtin_amdgcn_mfma_f32_32x32x16_bf16(pa3, PK(l3, h3), od, 0, 0, 0);
;     ...
; }
; DI void pv_d0(f32x16* o, int vb, bf16x8 pa0, bf16x8 pa1, bf16x8 pa2, bf16x8 pa3) {
;   pv_one<0>(o[0], vb, pa0, pa1, pa2, pa3); pv_one<1>(o[1], vb, pa0, pa1, pa2, pa3); pv_one<2>(o[2], vb, pa0, pa1, pa2, pa3); pv_one<3>(o[3], vb, pa0, pa1, pa2, pa3);
.LBB0_788:
	ds_read_b64_tr_b16 v[162:163], v169 offset:0x0
	ds_read_b64_tr_b16 v[164:165], v169 offset:0x800
	ds_read_b64_tr_b16 v[186:187], v169 offset:0x1000
	ds_read_b64_tr_b16 v[188:189], v169 offset:0x1800
	ds_read_b64_tr_b16 v[190:191], v169 offset:0x2000
	ds_read_b64_tr_b16 v[192:193], v169 offset:0x2800
	ds_read_b64_tr_b16 v[194:195], v169 offset:0x3000
	ds_read_b64_tr_b16 v[196:197], v169 offset:0x3800
	s_waitcnt lgkmcnt(0)
	v_mfma_f32_32x32x16_bf16 v[2:17], v[138:141], v[162:165], v[2:17]
	ds_read_b64_tr_b16 v[162:163], v169 offset:0x200
	ds_read_b64_tr_b16 v[164:165], v169 offset:0xa00
	v_max3_f32 v203, v82, v83, v84
	v_max3_f32 v204, v85, v86, v87
	v_max3_f32 v203, v203, v88, v89
	v_max3_f32 v204, v204, v90, v91
	v_max3_f32 v203, v203, v92, v93
	v_max3_f32 v204, v204, v94, v95
	v_mfma_f32_32x32x16_bf16 v[2:17], v[142:145], v[186:189], v[2:17]
	ds_read_b64_tr_b16 v[186:187], v169 offset:0x1200
	ds_read_b64_tr_b16 v[188:189], v169 offset:0x1a00
	v_max3_f32 v203, v203, v96, v97
	v_max3_f32 v204, v204, v66, v67
	v_max3_f32 v203, v203, v68, v69
	v_max3_f32 v204, v204, v70, v71
	v_max3_f32 v203, v203, v72, v73
	v_max3_f32 v204, v204, v74, v75
	v_mfma_f32_32x32x16_bf16 v[2:17], v[146:149], v[190:193], v[2:17]
	ds_read_b64_tr_b16 v[190:191], v169 offset:0x2200
	ds_read_b64_tr_b16 v[192:193], v169 offset:0x2a00
	v_max3_f32 v203, v203, v76, v77
	v_max3_f32 v204, v204, v78, v79
	v_max3_f32 v203, v203, v80, v81
	v_max_f32_e32 v203, v203, v204
	v_mov_b32_e32 v204, v203
	v_mfma_f32_32x32x16_bf16 v[2:17], v[150:153], v[194:197], v[2:17]
	ds_read_b64_tr_b16 v[194:195], v169 offset:0x3200
	ds_read_b64_tr_b16 v[196:197], v169 offset:0x3a00
	v_permlane32_swap_b32_e32 v203, v204
	v_max_f32_e32 v203, v203, v204
	v_sub_f32_e32 v204, v203, v183
	v_cmp_ge_f32_e32 vcc, s26, v204
	v_max_f32_e32 v203, v183, v203
	v_sub_f32_e32 v204, v183, v203
	s_waitcnt lgkmcnt(0)
	v_mfma_f32_32x32x16_bf16 v[50:65], v[138:141], v[162:165], v[50:65]
	ds_read_b64_tr_b16 v[162:163], v169 offset:0x400
	ds_read_b64_tr_b16 v[164:165], v169 offset:0xc00
	v_mul_f32_e32 v204, 0x3e38aa3b, v204
	v_exp_f32_e32 v204, v204
	s_cmp_eq_u64 vcc, exec
	s_cselect_b64 s[2:3], -1, 0
	v_mfma_f32_32x32x16_bf16 v[50:65], v[142:145], v[186:189], v[50:65]
	ds_read_b64_tr_b16 v[186:187], v169 offset:0x1400
	ds_read_b64_tr_b16 v[188:189], v169 offset:0x1c00
	v_cndmask_b32_e64 v202, v203, v183, s[2:3]
	v_mul_f32_e32 v202, 0xbe38aa3b, v202
	v_fmamk_f32 v208, v82, 0x3e38aa3b, v202
	v_fmamk_f32 v209, v83, 0x3e38aa3b, v202
	v_fmamk_f32 v210, v84, 0x3e38aa3b, v202
	v_mfma_f32_32x32x16_bf16 v[50:65], v[146:149], v[190:193], v[50:65]
	ds_read_b64_tr_b16 v[190:191], v169 offset:0x2400
	ds_read_b64_tr_b16 v[192:193], v169 offset:0x2c00
	v_fmamk_f32 v211, v85, 0x3e38aa3b, v202
	v_fmamk_f32 v214, v86, 0x3e38aa3b, v202
	v_fmamk_f32 v215, v87, 0x3e38aa3b, v202
	v_exp_f32_e32 v208, v208
	v_exp_f32_e32 v209, v209
	v_exp_f32_e32 v210, v210
	v_mfma_f32_32x32x16_bf16 v[50:65], v[150:153], v[194:197], v[50:65]
	ds_read_b64_tr_b16 v[194:195], v169 offset:0x3400
	ds_read_b64_tr_b16 v[196:197], v169 offset:0x3c00
	v_fmamk_f32 v216, v88, 0x3e38aa3b, v202
	v_fmamk_f32 v217, v89, 0x3e38aa3b, v202
	v_fmamk_f32 v218, v90, 0x3e38aa3b, v202
	v_exp_f32_e32 v211, v211
	v_exp_f32_e32 v214, v214
	v_exp_f32_e32 v215, v215
	s_waitcnt lgkmcnt(0)
	v_mfma_f32_32x32x16_bf16 v[34:49], v[138:141], v[162:165], v[34:49]
	ds_read_b64_tr_b16 v[162:163], v169 offset:0x600
	ds_read_b64_tr_b16 v[164:165], v169 offset:0xe00
	v_fmamk_f32 v219, v91, 0x3e38aa3b, v202
	v_fmamk_f32 v220, v92, 0x3e38aa3b, v202
	v_fmamk_f32 v221, v93, 0x3e38aa3b, v202
	v_exp_f32_e32 v216, v216
	v_exp_f32_e32 v217, v217
	v_exp_f32_e32 v218, v218
	v_mfma_f32_32x32x16_bf16 v[34:49], v[142:145], v[186:189], v[34:49]
	ds_read_b64_tr_b16 v[186:187], v169 offset:0x1600
	ds_read_b64_tr_b16 v[188:189], v169 offset:0x1e00
	v_fmamk_f32 v222, v94, 0x3e38aa3b, v202
	v_fmamk_f32 v223, v95, 0x3e38aa3b, v202
	v_fmamk_f32 v224, v96, 0x3e38aa3b, v202
	v_exp_f32_e32 v219, v219
	v_exp_f32_e32 v220, v220
	v_exp_f32_e32 v221, v221
	v_mfma_f32_32x32x16_bf16 v[34:49], v[146:149], v[190:193], v[34:49]
	ds_read_b64_tr_b16 v[190:191], v169 offset:0x2600
	ds_read_b64_tr_b16 v[192:193], v169 offset:0x2e00
	v_fmamk_f32 v225, v97, 0x3e38aa3b, v202
	v_fmamk_f32 v226, v66, 0x3e38aa3b, v202
	v_fmamk_f32 v227, v67, 0x3e38aa3b, v202
	v_exp_f32_e32 v222, v222
	v_exp_f32_e32 v223, v223
	v_exp_f32_e32 v224, v224
	v_mfma_f32_32x32x16_bf16 v[34:49], v[150:153], v[194:197], v[34:49]
	ds_read_b64_tr_b16 v[194:195], v169 offset:0x3600
	ds_read_b64_tr_b16 v[196:197], v169 offset:0x3e00
	v_fmamk_f32 v228, v68, 0x3e38aa3b, v202
	v_fmamk_f32 v229, v69, 0x3e38aa3b, v202
	v_fmamk_f32 v230, v70, 0x3e38aa3b, v202
	v_exp_f32_e32 v225, v225
	v_exp_f32_e32 v226, v226
	v_exp_f32_e32 v227, v227
	s_waitcnt lgkmcnt(0)
	v_mfma_f32_32x32x16_bf16 v[18:33], v[138:141], v[162:165], v[18:33]
	v_fmamk_f32 v231, v71, 0x3e38aa3b, v202
	v_fmamk_f32 v244, v72, 0x3e38aa3b, v202
	v_fmamk_f32 v245, v73, 0x3e38aa3b, v202
	v_exp_f32_e32 v228, v228
	v_exp_f32_e32 v229, v229
	v_exp_f32_e32 v230, v230
	v_mfma_f32_32x32x16_bf16 v[18:33], v[142:145], v[186:189], v[18:33]
	v_fmamk_f32 v246, v74, 0x3e38aa3b, v202
	v_fmamk_f32 v247, v75, 0x3e38aa3b, v202
	v_fmamk_f32 v248, v76, 0x3e38aa3b, v202
	v_exp_f32_e32 v231, v231
	v_exp_f32_e32 v244, v244
	v_exp_f32_e32 v245, v245
	v_mfma_f32_32x32x16_bf16 v[18:33], v[146:149], v[190:193], v[18:33]
	v_fmamk_f32 v249, v77, 0x3e38aa3b, v202
	v_fmamk_f32 v250, v78, 0x3e38aa3b, v202
	v_fmamk_f32 v251, v79, 0x3e38aa3b, v202
	v_exp_f32_e32 v246, v246
	v_exp_f32_e32 v247, v247
	v_exp_f32_e32 v248, v248
	v_mfma_f32_32x32x16_bf16 v[18:33], v[150:153], v[194:197], v[18:33]
	v_fmamk_f32 v252, v80, 0x3e38aa3b, v202
	v_fmac_f32_e32 v202, 0x3e38aa3b, v81
	v_exp_f32_e32 v249, v249
	v_exp_f32_e32 v250, v250
	v_exp_f32_e32 v251, v251
	v_exp_f32_e32 v252, v252
	v_exp_f32_e32 v202, v202
	v_cndmask_b32_e64 v142, v203, v183, s[2:3]
	s_barrier
; #define SWRITE(b, i) do { *(LAS bf16x8*)(V_lds + (b) * SHM_V + vst0) = sr_[i].vs0; *(LAS bf16x8*)(V_lds + (b) * SHM_V + vst1) = sr_[i].vs1; \
;     _Pragma("unroll") for (int _c = 0; _c < NKC; ++_c) *(LAS bf16x8*)(K_lds + (b) * SHM_K + kswz<DQK>(krow[_c], kcol[_c] * 2)) = sr_[i].ks[_c]; } while (0)
; #define SWAIT() do { if constexpr (SDEPTH == 2) { if constexpr (NKC == 1) asm volatile("s_waitcnt vmcnt(3)" ::: "memory"); else if constexpr (NKC == 2) asm volatile("s_waitcnt vmcnt(4)" ::: "memory"); else asm volatile("s_waitcnt vmcnt(5)" ::: "memory"); } \
;     else asm volatile("s_waitcnt vmcnt(0)" ::: "memory"); } while (0)
; #define RESC(a) do { if (__any((a) < 1.f)) { if (hi == 0) al_l[r32] = (a); asm volatile("s_waitcnt lgkmcnt(0)" ::: "memory"); \
;     _Pragma("unroll") for (int d = 0; d < 4; ++d) _Pragma("unroll") for (int r = 0; r < 16; ++r) o[d][r] *= al_l[crow(r, hi)]; } } while (0)
; template <int DQK, int SDEPTH, bool OUT_BF16, int QREG = DQK / 16, bool OUT_F16 = false> ...
;     ...
;     __syncthreads(); SWAIT(); SWRITE(1, SO);
;     RESC(alA); __syncthreads();
	s_waitcnt vmcnt(3)
	v_cndmask_b32_e64 v143, v204, 1.0, s[2:3]
	v_cmp_gt_f32_e32 vcc, 1.0, v143
	s_waitcnt vmcnt(2)
	ds_write_b128 v172, v[126:129] offset:16384
	s_waitcnt vmcnt(1)
	ds_write_b128 v173, v[130:133] offset:16384
	s_waitcnt vmcnt(0)
	ds_write_b128 v174, v[134:137] offset:40960
	s_cbranch_vccz .LBB0_792
	s_and_saveexec_b64 s[12:13], s[0:1]
	ds_write_b32 v168, v143 offset:49280
	s_or_b64 exec, exec, s[12:13]
	s_waitcnt lgkmcnt(0)
	v_add_u32_e32 v139, v157, v0
	ds_read_b128 v[126:129], v139 offset:49376
	ds_read_b128 v[130:133], v139 offset:49344
	ds_read_b128 v[134:137], v139 offset:49312
	ds_read_b128 v[144:147], v139 offset:49280
	s_waitcnt lgkmcnt(3)
	v_pk_mul_f32 v[14:15], v[14:15], v[126:127]
	s_waitcnt lgkmcnt(2)
	v_pk_mul_f32 v[10:11], v[10:11], v[130:131]
	s_waitcnt lgkmcnt(1)
	v_pk_mul_f32 v[6:7], v[6:7], v[134:135]
	v_pk_mul_f32 v[16:17], v[16:17], v[128:129]
	v_pk_mul_f32 v[12:13], v[12:13], v[132:133]
	v_pk_mul_f32 v[8:9], v[8:9], v[136:137]
	s_waitcnt lgkmcnt(0)
	v_pk_mul_f32 v[4:5], v[4:5], v[146:147]
	v_pk_mul_f32 v[2:3], v[2:3], v[144:145]
	v_pk_mul_f32 v[62:63], v[62:63], v[126:127]
	v_pk_mul_f32 v[58:59], v[58:59], v[130:131]
	v_pk_mul_f32 v[54:55], v[54:55], v[134:135]
	v_pk_mul_f32 v[64:65], v[64:65], v[128:129]
	v_pk_mul_f32 v[60:61], v[60:61], v[132:133]
	v_pk_mul_f32 v[56:57], v[56:57], v[136:137]
	v_pk_mul_f32 v[52:53], v[52:53], v[146:147]
	v_pk_mul_f32 v[50:51], v[50:51], v[144:145]
	v_pk_mul_f32 v[46:47], v[46:47], v[126:127]
	v_pk_mul_f32 v[42:43], v[42:43], v[130:131]
	v_pk_mul_f32 v[38:39], v[38:39], v[134:135]
	v_pk_mul_f32 v[48:49], v[48:49], v[128:129]
	v_pk_mul_f32 v[44:45], v[44:45], v[132:133]
	v_pk_mul_f32 v[40:41], v[40:41], v[136:137]
	v_pk_mul_f32 v[36:37], v[36:37], v[146:147]
	v_pk_mul_f32 v[34:35], v[34:35], v[144:145]
	v_pk_mul_f32 v[30:31], v[30:31], v[126:127]
	v_pk_mul_f32 v[26:27], v[26:27], v[130:131]
	v_pk_mul_f32 v[22:23], v[22:23], v[134:135]
	v_pk_mul_f32 v[32:33], v[32:33], v[128:129]
	v_pk_mul_f32 v[28:29], v[28:29], v[132:133]
	v_pk_mul_f32 v[24:25], v[24:25], v[136:137]
	v_pk_mul_f32 v[20:21], v[20:21], v[146:147]
	v_pk_mul_f32 v[18:19], v[18:19], v[144:145]
